# super-phases 1 and 3: MFMA-opening barrier after the first 8 MFMAs (was 4)
# baseline (speedup 1.0000x reference)
.LBB0_233:
	ds_read_b128 v[130:133], v213
	ds_read_b128 v[134:137], v214
	ds_read_b128 v[138:141], v215
	ds_read_b128 v[142:145], v216
	ds_read_b128 v[146:149], v217
	ds_read_b128 v[150:153], v218
	ds_read_b128 v[154:157], v219
	ds_read_b128 v[158:161], v220
	s_add_i32 s4, s33, 0xffffe080
	s_cmp_eq_u32 s58, 12
	s_cselect_b32 s61, s18, s4
	s_cselect_b32 s60, s19, s57
	s_add_i32 s59, s61, 0x80
	s_mov_b32 s4, s70
	s_mov_b32 m0, s38
	ds_read_b128 v[162:165], v221
	ds_read_b128 v[166:169], v221 offset:2048
	ds_read_b128 v[170:173], v222
	ds_read_b128 v[174:177], v222 offset:2048
	ds_read_b128 v[178:181], v221 offset:4096
	ds_read_b128 v[182:185], v221 offset:6144
	ds_read_b128 v[186:189], v222 offset:4096
	ds_read_b128 v[190:193], v222 offset:6144
	buffer_load_dwordx4 v207, s[4:7], s33 offen lds
	s_mov_b32 m0, s41
	s_nop 0
	buffer_load_dwordx4 v209, s[4:7], s33 offen lds
	s_waitcnt vmcnt(8)
	s_waitcnt lgkmcnt(0)
	s_setprio 1
	v_mfma_f32_16x16x32_bf16 v[114:117], v[130:133], v[162:165], v[114:117]
	v_mfma_f32_16x16x32_bf16 v[110:113], v[138:141], v[162:165], v[110:113]
	v_mfma_f32_16x16x32_bf16 v[106:109], v[130:133], v[166:169], v[106:109]
	v_mfma_f32_16x16x32_bf16 v[102:105], v[138:141], v[166:169], v[102:105]
	v_mfma_f32_16x16x32_bf16 v[98:101], v[130:133], v[178:181], v[98:101]
	v_mfma_f32_16x16x32_bf16 v[94:97], v[138:141], v[178:181], v[94:97]
	v_mfma_f32_16x16x32_bf16 v[90:93], v[130:133], v[182:185], v[90:93]
	v_mfma_f32_16x16x32_bf16 v[86:89], v[138:141], v[182:185], v[86:89]
	s_barrier
	v_mfma_f32_16x16x32_bf16 v[114:117], v[134:137], v[170:173], v[114:117]
	v_mfma_f32_16x16x32_bf16 v[110:113], v[142:145], v[170:173], v[110:113]
	v_mfma_f32_16x16x32_bf16 v[106:109], v[134:137], v[174:177], v[106:109]
	v_mfma_f32_16x16x32_bf16 v[102:105], v[142:145], v[174:177], v[102:105]
	v_mfma_f32_16x16x32_bf16 v[98:101], v[134:137], v[186:189], v[98:101]
	v_mfma_f32_16x16x32_bf16 v[94:97], v[142:145], v[186:189], v[94:97]
	v_mfma_f32_16x16x32_bf16 v[90:93], v[134:137], v[190:193], v[90:93]
	v_mfma_f32_16x16x32_bf16 v[86:89], v[142:145], v[190:193], v[86:89]
	v_mfma_f32_16x16x32_bf16 v[82:85], v[146:149], v[162:165], v[82:85]
	v_mfma_f32_16x16x32_bf16 v[74:77], v[154:157], v[162:165], v[74:77]
	v_mfma_f32_16x16x32_bf16 v[70:73], v[146:149], v[166:169], v[70:73]
	v_mfma_f32_16x16x32_bf16 v[66:69], v[154:157], v[166:169], v[66:69]
	v_mfma_f32_16x16x32_bf16 v[62:65], v[146:149], v[178:181], v[62:65]
	v_mfma_f32_16x16x32_bf16 v[58:61], v[154:157], v[178:181], v[58:61]
	v_mfma_f32_16x16x32_bf16 v[54:57], v[146:149], v[182:185], v[54:57]
	v_mfma_f32_16x16x32_bf16 v[50:53], v[154:157], v[182:185], v[50:53]
	v_mfma_f32_16x16x32_bf16 v[82:85], v[150:153], v[170:173], v[82:85]
	v_mfma_f32_16x16x32_bf16 v[74:77], v[158:161], v[170:173], v[74:77]
	v_mfma_f32_16x16x32_bf16 v[70:73], v[150:153], v[174:177], v[70:73]
	v_mfma_f32_16x16x32_bf16 v[66:69], v[158:161], v[174:177], v[66:69]
	v_mfma_f32_16x16x32_bf16 v[62:65], v[150:153], v[186:189], v[62:65]
	v_mfma_f32_16x16x32_bf16 v[58:61], v[158:161], v[186:189], v[58:61]
	v_mfma_f32_16x16x32_bf16 v[54:57], v[150:153], v[190:193], v[54:57]
	v_mfma_f32_16x16x32_bf16 v[50:53], v[158:161], v[190:193], v[50:53]
	s_barrier
	s_setprio 0
	s_mov_b32 m0, s21
	ds_read_b128 v[162:165], v221 offset:16384
	ds_read_b128 v[166:169], v221 offset:18432
	ds_read_b128 v[170:173], v222 offset:16384
	ds_read_b128 v[174:177], v222 offset:18432
	ds_read_b128 v[178:181], v221 offset:20480
	ds_read_b128 v[182:185], v221 offset:22528
	ds_read_b128 v[186:189], v222 offset:20480
	ds_read_b128 v[190:193], v222 offset:22528
	buffer_load_dwordx4 v208, s[4:7], s60 offen lds
	s_mov_b32 m0, s22
	s_add_i32 s62, s60, 0x40000
	buffer_load_dwordx4 v210, s[4:7], s60 offen lds
	s_mov_b32 m0, s23
	s_nop 0
	buffer_load_dwordx4 v208, s[4:7], s62 offen lds
	s_mov_b32 m0, s24
	s_nop 0
	buffer_load_dwordx4 v210, s[4:7], s62 offen lds
	s_mov_b32 m0, s20
	s_nop 0
	buffer_load_dwordx4 v207, s[4:7], s61 offen lds
	s_mov_b32 m0, s25
	s_nop 0
	buffer_load_dwordx4 v209, s[4:7], s61 offen lds
	s_waitcnt vmcnt(8)
	s_waitcnt lgkmcnt(0)
	s_setprio 1
	s_barrier
	v_mfma_f32_16x16x32_bf16 v[78:81], v[130:133], v[162:165], v[78:81]
	v_mfma_f32_16x16x32_bf16 v[46:49], v[138:141], v[162:165], v[46:49]
	v_mfma_f32_16x16x32_bf16 v[42:45], v[130:133], v[166:169], v[42:45]
	v_mfma_f32_16x16x32_bf16 v[38:41], v[138:141], v[166:169], v[38:41]
	v_mfma_f32_16x16x32_bf16 v[34:37], v[130:133], v[178:181], v[34:37]
	v_mfma_f32_16x16x32_bf16 v[30:33], v[138:141], v[178:181], v[30:33]
	v_mfma_f32_16x16x32_bf16 v[26:29], v[130:133], v[182:185], v[26:29]
	v_mfma_f32_16x16x32_bf16 v[22:25], v[138:141], v[182:185], v[22:25]
	v_mfma_f32_16x16x32_bf16 v[78:81], v[134:137], v[170:173], v[78:81]
	v_mfma_f32_16x16x32_bf16 v[46:49], v[142:145], v[170:173], v[46:49]
	v_mfma_f32_16x16x32_bf16 v[42:45], v[134:137], v[174:177], v[42:45]
	v_mfma_f32_16x16x32_bf16 v[38:41], v[142:145], v[174:177], v[38:41]
	v_mfma_f32_16x16x32_bf16 v[34:37], v[134:137], v[186:189], v[34:37]
	v_mfma_f32_16x16x32_bf16 v[30:33], v[142:145], v[186:189], v[30:33]
	v_mfma_f32_16x16x32_bf16 v[26:29], v[134:137], v[190:193], v[26:29]
	v_mfma_f32_16x16x32_bf16 v[22:25], v[142:145], v[190:193], v[22:25]
	v_mfma_f32_16x16x32_bf16 v[18:21], v[146:149], v[162:165], v[18:21]
	v_mfma_f32_16x16x32_bf16 v[14:17], v[154:157], v[162:165], v[14:17]
	v_mfma_f32_16x16x32_bf16 v[10:13], v[146:149], v[166:169], v[10:13]
	v_mfma_f32_16x16x32_bf16 v[6:9], v[154:157], v[166:169], v[6:9]
	v_mfma_f32_16x16x32_bf16 v[2:5], v[146:149], v[178:181], v[2:5]
	v_mfma_f32_16x16x32_bf16 v[126:129], v[154:157], v[178:181], v[126:129]
	v_mfma_f32_16x16x32_bf16 v[122:125], v[146:149], v[182:185], v[122:125]
	v_mfma_f32_16x16x32_bf16 v[118:121], v[154:157], v[182:185], v[118:121]
	v_mfma_f32_16x16x32_bf16 v[18:21], v[150:153], v[170:173], v[18:21]
	v_mfma_f32_16x16x32_bf16 v[14:17], v[158:161], v[170:173], v[14:17]
	v_mfma_f32_16x16x32_bf16 v[10:13], v[150:153], v[174:177], v[10:13]
	v_mfma_f32_16x16x32_bf16 v[6:9], v[158:161], v[174:177], v[6:9]
	v_mfma_f32_16x16x32_bf16 v[2:5], v[150:153], v[186:189], v[2:5]
	v_mfma_f32_16x16x32_bf16 v[126:129], v[158:161], v[186:189], v[126:129]
	v_mfma_f32_16x16x32_bf16 v[122:125], v[150:153], v[190:193], v[122:125]
	v_mfma_f32_16x16x32_bf16 v[118:121], v[158:161], v[190:193], v[118:121]
	s_barrier
	s_setprio 0
	ds_read_b128 v[130:133], v194
	ds_read_b128 v[134:137], v224
	ds_read_b128 v[138:141], v225
	ds_read_b128 v[142:145], v228
	ds_read_b128 v[146:149], v229
	ds_read_b128 v[150:153], v230
	ds_read_b128 v[154:157], v231
	ds_read_b128 v[158:161], v233
	s_addk_i32 s61, 0x2000
	s_mov_b32 m0, s26
	ds_read_b128 v[162:165], v221 offset:32768
	ds_read_b128 v[166:169], v221 offset:34816
	ds_read_b128 v[170:173], v222 offset:32768
	ds_read_b128 v[174:177], v222 offset:34816
	ds_read_b128 v[178:181], v221 offset:36864
	ds_read_b128 v[182:185], v221 offset:38912
	ds_read_b128 v[186:189], v222 offset:36864
	ds_read_b128 v[190:193], v222 offset:38912
	buffer_load_dwordx4 v207, s[4:7], s61 offen lds
	s_mov_b32 m0, s27
	s_nop 0
	buffer_load_dwordx4 v209, s[4:7], s61 offen lds
	s_waitcnt vmcnt(8)
	s_waitcnt lgkmcnt(0)
	s_setprio 1
	v_mfma_f32_16x16x32_bf16 v[114:117], v[130:133], v[162:165], v[114:117]
	v_mfma_f32_16x16x32_bf16 v[110:113], v[138:141], v[162:165], v[110:113]
	v_mfma_f32_16x16x32_bf16 v[106:109], v[130:133], v[166:169], v[106:109]
	v_mfma_f32_16x16x32_bf16 v[102:105], v[138:141], v[166:169], v[102:105]
	v_mfma_f32_16x16x32_bf16 v[98:101], v[130:133], v[178:181], v[98:101]
	v_mfma_f32_16x16x32_bf16 v[94:97], v[138:141], v[178:181], v[94:97]
	v_mfma_f32_16x16x32_bf16 v[90:93], v[130:133], v[182:185], v[90:93]
	v_mfma_f32_16x16x32_bf16 v[86:89], v[138:141], v[182:185], v[86:89]
	s_barrier
	v_mfma_f32_16x16x32_bf16 v[114:117], v[134:137], v[170:173], v[114:117]
	v_mfma_f32_16x16x32_bf16 v[110:113], v[142:145], v[170:173], v[110:113]
	v_mfma_f32_16x16x32_bf16 v[106:109], v[134:137], v[174:177], v[106:109]
	v_mfma_f32_16x16x32_bf16 v[102:105], v[142:145], v[174:177], v[102:105]
	v_mfma_f32_16x16x32_bf16 v[98:101], v[134:137], v[186:189], v[98:101]
	v_mfma_f32_16x16x32_bf16 v[94:97], v[142:145], v[186:189], v[94:97]
	v_mfma_f32_16x16x32_bf16 v[90:93], v[134:137], v[190:193], v[90:93]
	v_mfma_f32_16x16x32_bf16 v[86:89], v[142:145], v[190:193], v[86:89]
	v_mfma_f32_16x16x32_bf16 v[82:85], v[146:149], v[162:165], v[82:85]
	v_mfma_f32_16x16x32_bf16 v[74:77], v[154:157], v[162:165], v[74:77]
	v_mfma_f32_16x16x32_bf16 v[70:73], v[146:149], v[166:169], v[70:73]
	v_mfma_f32_16x16x32_bf16 v[66:69], v[154:157], v[166:169], v[66:69]
	v_mfma_f32_16x16x32_bf16 v[62:65], v[146:149], v[178:181], v[62:65]
	v_mfma_f32_16x16x32_bf16 v[58:61], v[154:157], v[178:181], v[58:61]
	v_mfma_f32_16x16x32_bf16 v[54:57], v[146:149], v[182:185], v[54:57]
	v_mfma_f32_16x16x32_bf16 v[50:53], v[154:157], v[182:185], v[50:53]
	v_mfma_f32_16x16x32_bf16 v[82:85], v[150:153], v[170:173], v[82:85]
	v_mfma_f32_16x16x32_bf16 v[74:77], v[158:161], v[170:173], v[74:77]
	v_mfma_f32_16x16x32_bf16 v[70:73], v[150:153], v[174:177], v[70:73]
	v_mfma_f32_16x16x32_bf16 v[66:69], v[158:161], v[174:177], v[66:69]
	v_mfma_f32_16x16x32_bf16 v[62:65], v[150:153], v[186:189], v[62:65]
	v_mfma_f32_16x16x32_bf16 v[58:61], v[158:161], v[186:189], v[58:61]
	v_mfma_f32_16x16x32_bf16 v[54:57], v[150:153], v[190:193], v[54:57]
	v_mfma_f32_16x16x32_bf16 v[50:53], v[158:161], v[190:193], v[50:53]
	s_barrier
	s_setprio 0
	s_mov_b32 m0, s29
	s_add_i32 s61, s60, 0x80
	ds_read_b128 v[162:165], v221 offset:49152
	ds_read_b128 v[166:169], v221 offset:51200
	ds_read_b128 v[170:173], v222 offset:49152
	ds_read_b128 v[174:177], v222 offset:51200
	ds_read_b128 v[178:181], v221 offset:53248
	ds_read_b128 v[182:185], v221 offset:55296
	ds_read_b128 v[186:189], v222 offset:53248
	ds_read_b128 v[190:193], v222 offset:55296
	buffer_load_dwordx4 v208, s[4:7], s61 offen lds
	s_mov_b32 m0, s30
	s_add_i32 s60, s60, 0x40080
	buffer_load_dwordx4 v210, s[4:7], s61 offen lds
	s_mov_b32 m0, s35
	s_nop 0
	buffer_load_dwordx4 v208, s[4:7], s60 offen lds
	s_mov_b32 m0, s36
	s_nop 0
	buffer_load_dwordx4 v210, s[4:7], s60 offen lds
	s_mov_b32 m0, s31
	s_nop 0
	buffer_load_dwordx4 v207, s[4:7], s59 offen lds
	s_mov_b32 m0, s34
	s_nop 0
	buffer_load_dwordx4 v209, s[4:7], s59 offen lds
	s_waitcnt vmcnt(8)
	s_waitcnt lgkmcnt(0)
	s_setprio 1
	s_barrier
	v_mfma_f32_16x16x32_bf16 v[78:81], v[130:133], v[162:165], v[78:81]
	v_mfma_f32_16x16x32_bf16 v[46:49], v[138:141], v[162:165], v[46:49]
	v_mfma_f32_16x16x32_bf16 v[42:45], v[130:133], v[166:169], v[42:45]
	v_mfma_f32_16x16x32_bf16 v[38:41], v[138:141], v[166:169], v[38:41]
	v_mfma_f32_16x16x32_bf16 v[34:37], v[130:133], v[178:181], v[34:37]
	v_mfma_f32_16x16x32_bf16 v[30:33], v[138:141], v[178:181], v[30:33]
	v_mfma_f32_16x16x32_bf16 v[26:29], v[130:133], v[182:185], v[26:29]
	v_mfma_f32_16x16x32_bf16 v[22:25], v[138:141], v[182:185], v[22:25]
	v_mfma_f32_16x16x32_bf16 v[78:81], v[134:137], v[170:173], v[78:81]
	v_mfma_f32_16x16x32_bf16 v[46:49], v[142:145], v[170:173], v[46:49]
	v_mfma_f32_16x16x32_bf16 v[42:45], v[134:137], v[174:177], v[42:45]
	v_mfma_f32_16x16x32_bf16 v[38:41], v[142:145], v[174:177], v[38:41]
	v_mfma_f32_16x16x32_bf16 v[34:37], v[134:137], v[186:189], v[34:37]
	v_mfma_f32_16x16x32_bf16 v[30:33], v[142:145], v[186:189], v[30:33]
	v_mfma_f32_16x16x32_bf16 v[26:29], v[134:137], v[190:193], v[26:29]
	v_mfma_f32_16x16x32_bf16 v[22:25], v[142:145], v[190:193], v[22:25]
	v_mfma_f32_16x16x32_bf16 v[18:21], v[146:149], v[162:165], v[18:21]
	v_mfma_f32_16x16x32_bf16 v[14:17], v[154:157], v[162:165], v[14:17]
	v_mfma_f32_16x16x32_bf16 v[10:13], v[146:149], v[166:169], v[10:13]
	v_mfma_f32_16x16x32_bf16 v[6:9], v[154:157], v[166:169], v[6:9]
	v_mfma_f32_16x16x32_bf16 v[2:5], v[146:149], v[178:181], v[2:5]
	v_mfma_f32_16x16x32_bf16 v[126:129], v[154:157], v[178:181], v[126:129]
	v_mfma_f32_16x16x32_bf16 v[122:125], v[146:149], v[182:185], v[122:125]
	v_mfma_f32_16x16x32_bf16 v[118:121], v[154:157], v[182:185], v[118:121]
	v_mfma_f32_16x16x32_bf16 v[18:21], v[150:153], v[170:173], v[18:21]
	v_mfma_f32_16x16x32_bf16 v[14:17], v[158:161], v[170:173], v[14:17]
	v_mfma_f32_16x16x32_bf16 v[10:13], v[150:153], v[174:177], v[10:13]
	v_mfma_f32_16x16x32_bf16 v[6:9], v[158:161], v[174:177], v[6:9]
	v_mfma_f32_16x16x32_bf16 v[2:5], v[150:153], v[186:189], v[2:5]
	v_mfma_f32_16x16x32_bf16 v[126:129], v[158:161], v[186:189], v[126:129]
	v_mfma_f32_16x16x32_bf16 v[122:125], v[150:153], v[190:193], v[122:125]
	v_mfma_f32_16x16x32_bf16 v[118:121], v[158:161], v[190:193], v[118:121]
	s_barrier
	s_setprio 0
	s_add_i32 s58, s58, 2
	s_addk_i32 s33, 0x100
	s_addk_i32 s57, 0x100
	s_cmp_gt_u32 s58, 13
	s_cbranch_scc0 .LBB0_233
	s_and_b64 vcc, exec, s[16:17]
	s_cbranch_vccz .LBB0_236
	s_barrier

.LBB0_546:
	ds_read_b128 v[130:133], v211
	ds_read_b128 v[134:137], v212
	ds_read_b128 v[138:141], v213
	ds_read_b128 v[142:145], v214
	ds_read_b128 v[146:149], v215
	ds_read_b128 v[150:153], v216
	ds_read_b128 v[154:157], v217
	ds_read_b128 v[158:161], v218
	s_add_i32 s4, s62, 0x80
	s_cmp_eq_u32 s63, s78
	s_cselect_b32 s84, s64, s4
	s_cselect_b32 s82, s33, s59
	s_cselect_b32 s81, s65, s61
	s_cselect_b32 s80, s56, s60
	s_add_i32 s79, s84, 0x80
	s_add_i32 s83, s60, s62
	s_mov_b32 s4, s70
	s_mov_b32 m0, s43
	ds_read_b128 v[162:165], v219
	ds_read_b128 v[166:169], v219 offset:2048
	ds_read_b128 v[170:173], v220
	ds_read_b128 v[174:177], v220 offset:2048
	ds_read_b128 v[178:181], v219 offset:4096
	ds_read_b128 v[182:185], v219 offset:6144
	ds_read_b128 v[186:189], v220 offset:4096
	ds_read_b128 v[190:193], v220 offset:6144
	buffer_load_dwordx4 v194, s[4:7], s83 offen lds
	s_mov_b32 m0, s44
	s_nop 0
	buffer_load_dwordx4 v222, s[4:7], s83 offen lds
	s_waitcnt vmcnt(8)
	s_waitcnt lgkmcnt(0)
	s_setprio 1
	v_mfma_f32_16x16x32_bf16 v[126:129], v[130:133], v[162:165], v[126:129]
	v_mfma_f32_16x16x32_bf16 v[122:125], v[138:141], v[162:165], v[122:125]
	v_mfma_f32_16x16x32_bf16 v[118:121], v[130:133], v[166:169], v[118:121]
	v_mfma_f32_16x16x32_bf16 v[114:117], v[138:141], v[166:169], v[114:117]
	v_mfma_f32_16x16x32_bf16 v[110:113], v[130:133], v[178:181], v[110:113]
	v_mfma_f32_16x16x32_bf16 v[106:109], v[138:141], v[178:181], v[106:109]
	v_mfma_f32_16x16x32_bf16 v[102:105], v[130:133], v[182:185], v[102:105]
	v_mfma_f32_16x16x32_bf16 v[98:101], v[138:141], v[182:185], v[98:101]
	s_barrier
	v_mfma_f32_16x16x32_bf16 v[126:129], v[134:137], v[170:173], v[126:129]
	v_mfma_f32_16x16x32_bf16 v[122:125], v[142:145], v[170:173], v[122:125]
	v_mfma_f32_16x16x32_bf16 v[118:121], v[134:137], v[174:177], v[118:121]
	v_mfma_f32_16x16x32_bf16 v[114:117], v[142:145], v[174:177], v[114:117]
	v_mfma_f32_16x16x32_bf16 v[110:113], v[134:137], v[186:189], v[110:113]
	v_mfma_f32_16x16x32_bf16 v[106:109], v[142:145], v[186:189], v[106:109]
	v_mfma_f32_16x16x32_bf16 v[102:105], v[134:137], v[190:193], v[102:105]
	v_mfma_f32_16x16x32_bf16 v[98:101], v[142:145], v[190:193], v[98:101]
	v_mfma_f32_16x16x32_bf16 v[94:97], v[146:149], v[162:165], v[94:97]
	v_mfma_f32_16x16x32_bf16 v[90:93], v[154:157], v[162:165], v[90:93]
	v_mfma_f32_16x16x32_bf16 v[86:89], v[146:149], v[166:169], v[86:89]
	v_mfma_f32_16x16x32_bf16 v[82:85], v[154:157], v[166:169], v[82:85]
	v_mfma_f32_16x16x32_bf16 v[78:81], v[146:149], v[178:181], v[78:81]
	v_mfma_f32_16x16x32_bf16 v[74:77], v[154:157], v[178:181], v[74:77]
	v_mfma_f32_16x16x32_bf16 v[70:73], v[146:149], v[182:185], v[70:73]
	v_mfma_f32_16x16x32_bf16 v[66:69], v[154:157], v[182:185], v[66:69]
	v_mfma_f32_16x16x32_bf16 v[94:97], v[150:153], v[170:173], v[94:97]
	v_mfma_f32_16x16x32_bf16 v[90:93], v[158:161], v[170:173], v[90:93]
	v_mfma_f32_16x16x32_bf16 v[86:89], v[150:153], v[174:177], v[86:89]
	v_mfma_f32_16x16x32_bf16 v[82:85], v[158:161], v[174:177], v[82:85]
	v_mfma_f32_16x16x32_bf16 v[78:81], v[150:153], v[186:189], v[78:81]
	v_mfma_f32_16x16x32_bf16 v[74:77], v[158:161], v[186:189], v[74:77]
	v_mfma_f32_16x16x32_bf16 v[70:73], v[150:153], v[190:193], v[70:73]
	v_mfma_f32_16x16x32_bf16 v[66:69], v[158:161], v[190:193], v[66:69]
	s_barrier
	s_setprio 0
	s_cmp_eq_u32 s82, 0
	s_cselect_b64 s[82:83], -1, 0
	v_cndmask_b32_e64 v233, v200, 0, s[82:83]
	s_mov_b32 m0, s25
	v_sub_u32_e32 v233, v201, v233
	v_cndmask_b32_e64 v234, v203, 0, s[82:83]
	ds_read_b128 v[162:165], v219 offset:16384
	ds_read_b128 v[166:169], v219 offset:18432
	ds_read_b128 v[170:173], v220 offset:16384
	ds_read_b128 v[174:177], v220 offset:18432
	ds_read_b128 v[178:181], v219 offset:20480
	ds_read_b128 v[182:185], v219 offset:22528
	ds_read_b128 v[186:189], v220 offset:20480
	ds_read_b128 v[190:193], v220 offset:22528
	buffer_load_dwordx4 v233, s[4:7], s81 offen lds
	v_sub_u32_e32 v234, v204, v234
	s_mov_b32 m0, s26
	s_add_i32 s85, s81, s80
	buffer_load_dwordx4 v234, s[4:7], s81 offen lds
	s_mov_b32 m0, s27
	v_cndmask_b32_e64 v235, v205, 0, s[82:83]
	buffer_load_dwordx4 v233, s[4:7], s85 offen lds
	s_mov_b32 m0, s28
	v_sub_u32_e32 v235, v1, v235
	buffer_load_dwordx4 v234, s[4:7], s85 offen lds
	s_mov_b32 m0, s24
	v_cndmask_b32_e64 v236, v206, 0, s[82:83]
	buffer_load_dwordx4 v235, s[4:7], s84 offen lds
	v_sub_u32_e32 v236, v202, v236
	s_mov_b32 m0, s29
	s_nop 0
	buffer_load_dwordx4 v236, s[4:7], s84 offen lds
	s_waitcnt vmcnt(8)
	s_waitcnt lgkmcnt(0)
	s_setprio 1
	s_barrier
	v_mfma_f32_16x16x32_bf16 v[62:65], v[130:133], v[162:165], v[62:65]
	v_mfma_f32_16x16x32_bf16 v[58:61], v[138:141], v[162:165], v[58:61]
	v_mfma_f32_16x16x32_bf16 v[54:57], v[130:133], v[166:169], v[54:57]
	v_mfma_f32_16x16x32_bf16 v[50:53], v[138:141], v[166:169], v[50:53]
	v_mfma_f32_16x16x32_bf16 v[46:49], v[130:133], v[178:181], v[46:49]
	v_mfma_f32_16x16x32_bf16 v[42:45], v[138:141], v[178:181], v[42:45]
	v_mfma_f32_16x16x32_bf16 v[38:41], v[130:133], v[182:185], v[38:41]
	v_mfma_f32_16x16x32_bf16 v[34:37], v[138:141], v[182:185], v[34:37]
	v_mfma_f32_16x16x32_bf16 v[62:65], v[134:137], v[170:173], v[62:65]
	v_mfma_f32_16x16x32_bf16 v[58:61], v[142:145], v[170:173], v[58:61]
	v_mfma_f32_16x16x32_bf16 v[54:57], v[134:137], v[174:177], v[54:57]
	v_mfma_f32_16x16x32_bf16 v[50:53], v[142:145], v[174:177], v[50:53]
	v_mfma_f32_16x16x32_bf16 v[46:49], v[134:137], v[186:189], v[46:49]
	v_mfma_f32_16x16x32_bf16 v[42:45], v[142:145], v[186:189], v[42:45]
	v_mfma_f32_16x16x32_bf16 v[38:41], v[134:137], v[190:193], v[38:41]
	v_mfma_f32_16x16x32_bf16 v[34:37], v[142:145], v[190:193], v[34:37]
	v_mfma_f32_16x16x32_bf16 v[30:33], v[146:149], v[162:165], v[30:33]
	v_mfma_f32_16x16x32_bf16 v[26:29], v[154:157], v[162:165], v[26:29]
	v_mfma_f32_16x16x32_bf16 v[22:25], v[146:149], v[166:169], v[22:25]
	v_mfma_f32_16x16x32_bf16 v[18:21], v[154:157], v[166:169], v[18:21]
	v_mfma_f32_16x16x32_bf16 v[14:17], v[146:149], v[178:181], v[14:17]
	v_mfma_f32_16x16x32_bf16 v[10:13], v[154:157], v[178:181], v[10:13]
	v_mfma_f32_16x16x32_bf16 v[6:9], v[146:149], v[182:185], v[6:9]
	v_mfma_f32_16x16x32_bf16 v[2:5], v[154:157], v[182:185], v[2:5]
	v_mfma_f32_16x16x32_bf16 v[30:33], v[150:153], v[170:173], v[30:33]
	v_mfma_f32_16x16x32_bf16 v[26:29], v[158:161], v[170:173], v[26:29]
	v_mfma_f32_16x16x32_bf16 v[22:25], v[150:153], v[174:177], v[22:25]
	v_mfma_f32_16x16x32_bf16 v[18:21], v[158:161], v[174:177], v[18:21]
	v_mfma_f32_16x16x32_bf16 v[14:17], v[150:153], v[186:189], v[14:17]
	v_mfma_f32_16x16x32_bf16 v[10:13], v[158:161], v[186:189], v[10:13]
	v_mfma_f32_16x16x32_bf16 v[6:9], v[150:153], v[190:193], v[6:9]
	v_mfma_f32_16x16x32_bf16 v[2:5], v[158:161], v[190:193], v[2:5]
	s_barrier
	s_setprio 0
	ds_read_b128 v[130:133], v223
	ds_read_b128 v[134:137], v224
	ds_read_b128 v[138:141], v225
	ds_read_b128 v[142:145], v227
	ds_read_b128 v[146:149], v228
	ds_read_b128 v[150:153], v229
	ds_read_b128 v[154:157], v230
	ds_read_b128 v[158:161], v231
	s_add_i32 s84, s84, s80
	s_mov_b32 m0, s30
	ds_read_b128 v[162:165], v219 offset:32768
	ds_read_b128 v[166:169], v219 offset:34816
	ds_read_b128 v[170:173], v220 offset:32768
	ds_read_b128 v[174:177], v220 offset:34816
	ds_read_b128 v[178:181], v219 offset:36864
	ds_read_b128 v[182:185], v219 offset:38912
	ds_read_b128 v[186:189], v220 offset:36864
	ds_read_b128 v[190:193], v220 offset:38912
	buffer_load_dwordx4 v235, s[4:7], s84 offen lds
	s_mov_b32 m0, s31
	s_nop 0
	buffer_load_dwordx4 v236, s[4:7], s84 offen lds
	s_waitcnt vmcnt(8)
	s_waitcnt lgkmcnt(0)
	s_setprio 1
	v_mfma_f32_16x16x32_bf16 v[126:129], v[130:133], v[162:165], v[126:129]
	v_mfma_f32_16x16x32_bf16 v[122:125], v[138:141], v[162:165], v[122:125]
	v_mfma_f32_16x16x32_bf16 v[118:121], v[130:133], v[166:169], v[118:121]
	v_mfma_f32_16x16x32_bf16 v[114:117], v[138:141], v[166:169], v[114:117]
	v_mfma_f32_16x16x32_bf16 v[110:113], v[130:133], v[178:181], v[110:113]
	v_mfma_f32_16x16x32_bf16 v[106:109], v[138:141], v[178:181], v[106:109]
	v_mfma_f32_16x16x32_bf16 v[102:105], v[130:133], v[182:185], v[102:105]
	v_mfma_f32_16x16x32_bf16 v[98:101], v[138:141], v[182:185], v[98:101]
	s_barrier
	v_mfma_f32_16x16x32_bf16 v[126:129], v[134:137], v[170:173], v[126:129]
	v_mfma_f32_16x16x32_bf16 v[122:125], v[142:145], v[170:173], v[122:125]
	v_mfma_f32_16x16x32_bf16 v[118:121], v[134:137], v[174:177], v[118:121]
	v_mfma_f32_16x16x32_bf16 v[114:117], v[142:145], v[174:177], v[114:117]
	v_mfma_f32_16x16x32_bf16 v[110:113], v[134:137], v[186:189], v[110:113]
	v_mfma_f32_16x16x32_bf16 v[106:109], v[142:145], v[186:189], v[106:109]
	v_mfma_f32_16x16x32_bf16 v[102:105], v[134:137], v[190:193], v[102:105]
	v_mfma_f32_16x16x32_bf16 v[98:101], v[142:145], v[190:193], v[98:101]
	v_mfma_f32_16x16x32_bf16 v[94:97], v[146:149], v[162:165], v[94:97]
	v_mfma_f32_16x16x32_bf16 v[90:93], v[154:157], v[162:165], v[90:93]
	v_mfma_f32_16x16x32_bf16 v[86:89], v[146:149], v[166:169], v[86:89]
	v_mfma_f32_16x16x32_bf16 v[82:85], v[154:157], v[166:169], v[82:85]
	v_mfma_f32_16x16x32_bf16 v[78:81], v[146:149], v[178:181], v[78:81]
	v_mfma_f32_16x16x32_bf16 v[74:77], v[154:157], v[178:181], v[74:77]
	v_mfma_f32_16x16x32_bf16 v[70:73], v[146:149], v[182:185], v[70:73]
	v_mfma_f32_16x16x32_bf16 v[66:69], v[154:157], v[182:185], v[66:69]
	v_mfma_f32_16x16x32_bf16 v[94:97], v[150:153], v[170:173], v[94:97]
	v_mfma_f32_16x16x32_bf16 v[90:93], v[158:161], v[170:173], v[90:93]
	v_mfma_f32_16x16x32_bf16 v[86:89], v[150:153], v[174:177], v[86:89]
	v_mfma_f32_16x16x32_bf16 v[82:85], v[158:161], v[174:177], v[82:85]
	v_mfma_f32_16x16x32_bf16 v[78:81], v[150:153], v[186:189], v[78:81]
	v_mfma_f32_16x16x32_bf16 v[74:77], v[158:161], v[186:189], v[74:77]
	v_mfma_f32_16x16x32_bf16 v[70:73], v[150:153], v[190:193], v[70:73]
	v_mfma_f32_16x16x32_bf16 v[66:69], v[158:161], v[190:193], v[66:69]
	s_barrier
	s_setprio 0
	s_mov_b32 m0, s36
	s_addk_i32 s81, 0x80
	ds_read_b128 v[162:165], v219 offset:49152
	ds_read_b128 v[166:169], v219 offset:51200
	ds_read_b128 v[170:173], v220 offset:49152
	ds_read_b128 v[174:177], v220 offset:51200
	ds_read_b128 v[178:181], v219 offset:53248
	ds_read_b128 v[182:185], v219 offset:55296
	ds_read_b128 v[186:189], v220 offset:53248
	ds_read_b128 v[190:193], v220 offset:55296
	buffer_load_dwordx4 v233, s[4:7], s81 offen lds
	s_mov_b32 m0, s37
	s_nop 0
	buffer_load_dwordx4 v234, s[4:7], s81 offen lds
	s_add_i32 s81, s81, s80
	s_mov_b32 m0, s40
	s_nop 0
	buffer_load_dwordx4 v233, s[4:7], s81 offen lds
	s_mov_b32 m0, s41
	s_nop 0
	buffer_load_dwordx4 v234, s[4:7], s81 offen lds
	s_mov_b32 m0, s38
	s_nop 0
	buffer_load_dwordx4 v235, s[4:7], s79 offen lds
	s_mov_b32 m0, s39
	s_nop 0
	buffer_load_dwordx4 v236, s[4:7], s79 offen lds
	s_waitcnt vmcnt(8)
	s_waitcnt lgkmcnt(0)
	s_setprio 1
	s_barrier
	v_mfma_f32_16x16x32_bf16 v[62:65], v[130:133], v[162:165], v[62:65]
	v_mfma_f32_16x16x32_bf16 v[58:61], v[138:141], v[162:165], v[58:61]
	v_mfma_f32_16x16x32_bf16 v[54:57], v[130:133], v[166:169], v[54:57]
	v_mfma_f32_16x16x32_bf16 v[50:53], v[138:141], v[166:169], v[50:53]
	v_mfma_f32_16x16x32_bf16 v[46:49], v[130:133], v[178:181], v[46:49]
	v_mfma_f32_16x16x32_bf16 v[42:45], v[138:141], v[178:181], v[42:45]
	v_mfma_f32_16x16x32_bf16 v[38:41], v[130:133], v[182:185], v[38:41]
	v_mfma_f32_16x16x32_bf16 v[34:37], v[138:141], v[182:185], v[34:37]
	v_mfma_f32_16x16x32_bf16 v[62:65], v[134:137], v[170:173], v[62:65]
	v_mfma_f32_16x16x32_bf16 v[58:61], v[142:145], v[170:173], v[58:61]
	v_mfma_f32_16x16x32_bf16 v[54:57], v[134:137], v[174:177], v[54:57]
	v_mfma_f32_16x16x32_bf16 v[50:53], v[142:145], v[174:177], v[50:53]
	v_mfma_f32_16x16x32_bf16 v[46:49], v[134:137], v[186:189], v[46:49]
	v_mfma_f32_16x16x32_bf16 v[42:45], v[142:145], v[186:189], v[42:45]
	v_mfma_f32_16x16x32_bf16 v[38:41], v[134:137], v[190:193], v[38:41]
	v_mfma_f32_16x16x32_bf16 v[34:37], v[142:145], v[190:193], v[34:37]
	v_mfma_f32_16x16x32_bf16 v[30:33], v[146:149], v[162:165], v[30:33]
	v_mfma_f32_16x16x32_bf16 v[26:29], v[154:157], v[162:165], v[26:29]
	v_mfma_f32_16x16x32_bf16 v[22:25], v[146:149], v[166:169], v[22:25]
	v_mfma_f32_16x16x32_bf16 v[18:21], v[154:157], v[166:169], v[18:21]
	v_mfma_f32_16x16x32_bf16 v[14:17], v[146:149], v[178:181], v[14:17]
	v_mfma_f32_16x16x32_bf16 v[10:13], v[154:157], v[178:181], v[10:13]
	v_mfma_f32_16x16x32_bf16 v[6:9], v[146:149], v[182:185], v[6:9]
	v_mfma_f32_16x16x32_bf16 v[2:5], v[154:157], v[182:185], v[2:5]
	v_mfma_f32_16x16x32_bf16 v[30:33], v[150:153], v[170:173], v[30:33]
	v_mfma_f32_16x16x32_bf16 v[26:29], v[158:161], v[170:173], v[26:29]
	v_mfma_f32_16x16x32_bf16 v[22:25], v[150:153], v[174:177], v[22:25]
	v_mfma_f32_16x16x32_bf16 v[18:21], v[158:161], v[174:177], v[18:21]
	v_mfma_f32_16x16x32_bf16 v[14:17], v[150:153], v[186:189], v[14:17]
	v_mfma_f32_16x16x32_bf16 v[10:13], v[158:161], v[186:189], v[10:13]
	v_mfma_f32_16x16x32_bf16 v[6:9], v[150:153], v[190:193], v[6:9]
	v_mfma_f32_16x16x32_bf16 v[2:5], v[158:161], v[190:193], v[2:5]
	s_barrier
	s_setprio 0
	s_add_i32 s4, s78, 2
	s_addk_i32 s62, 0x100
	s_addk_i32 s61, 0x100
	s_cmp_ge_u32 s78, s63
	s_mov_b32 s78, s4
	s_cbranch_scc0 .LBB0_546
	s_and_b64 vcc, exec, s[12:13]
	s_cbranch_vccz .LBB0_549
	s_barrier

.LBB0_841:
	ds_read_b128 v[130:133], v240
	ds_read_b128 v[134:137], v241
	ds_read_b128 v[138:141], v242
	ds_read_b128 v[142:145], v243
	ds_read_b128 v[146:149], v244
	ds_read_b128 v[150:153], v245
	ds_read_b128 v[154:157], v246
	ds_read_b128 v[158:161], v247
	s_add_i32 s8, s42, s5
	s_add_i32 s19, s34, s5
	s_add_i32 s18, s8, 0x800
	s_addk_i32 s19, 0x800
	s_cmp_eq_u32 s5, 0
	s_cselect_b32 s20, s0, s18
	s_cselect_b32 s19, s1, s19
	s_add_i32 s18, s20, 0x80
	s_add_i32 s21, s8, 0x40780
	s_mov_b32 s8, s70
	s_mov_b32 m0, s52
	ds_read_b128 v[162:165], v248
	ds_read_b128 v[166:169], v248 offset:2048
	ds_read_b128 v[170:173], v249
	ds_read_b128 v[174:177], v249 offset:2048
	ds_read_b128 v[178:181], v248 offset:4096
	ds_read_b128 v[182:185], v248 offset:6144
	ds_read_b128 v[186:189], v249 offset:4096
	ds_read_b128 v[190:193], v249 offset:6144
	buffer_load_dwordx4 v1, s[8:11], s21 offen lds
	s_mov_b32 m0, s53
	s_nop 0
	buffer_load_dwordx4 v234, s[8:11], s21 offen lds
	s_waitcnt vmcnt(8)
	s_waitcnt lgkmcnt(0)
	s_setprio 1
	v_mfma_f32_16x16x32_bf16 v[74:77], v[130:133], v[162:165], v[74:77]
	v_mfma_f32_16x16x32_bf16 v[70:73], v[138:141], v[162:165], v[70:73]
	v_mfma_f32_16x16x32_bf16 v[66:69], v[130:133], v[166:169], v[66:69]
	v_mfma_f32_16x16x32_bf16 v[82:85], v[138:141], v[166:169], v[82:85]
	v_mfma_f32_16x16x32_bf16 v[78:81], v[130:133], v[178:181], v[78:81]
	v_mfma_f32_16x16x32_bf16 v[90:93], v[138:141], v[178:181], v[90:93]
	v_mfma_f32_16x16x32_bf16 v[86:89], v[130:133], v[182:185], v[86:89]
	v_mfma_f32_16x16x32_bf16 v[102:105], v[138:141], v[182:185], v[102:105]
	s_barrier
	v_mfma_f32_16x16x32_bf16 v[74:77], v[134:137], v[170:173], v[74:77]
	v_mfma_f32_16x16x32_bf16 v[70:73], v[142:145], v[170:173], v[70:73]
	v_mfma_f32_16x16x32_bf16 v[66:69], v[134:137], v[174:177], v[66:69]
	v_mfma_f32_16x16x32_bf16 v[82:85], v[142:145], v[174:177], v[82:85]
	v_mfma_f32_16x16x32_bf16 v[78:81], v[134:137], v[186:189], v[78:81]
	v_mfma_f32_16x16x32_bf16 v[90:93], v[142:145], v[186:189], v[90:93]
	v_mfma_f32_16x16x32_bf16 v[86:89], v[134:137], v[190:193], v[86:89]
	v_mfma_f32_16x16x32_bf16 v[102:105], v[142:145], v[190:193], v[102:105]
	v_mfma_f32_16x16x32_bf16 v[98:101], v[146:149], v[162:165], v[98:101]
	v_mfma_f32_16x16x32_bf16 v[94:97], v[154:157], v[162:165], v[94:97]
	v_mfma_f32_16x16x32_bf16 v[106:109], v[146:149], v[166:169], v[106:109]
	v_mfma_f32_16x16x32_bf16 v[110:113], v[154:157], v[166:169], v[110:113]
	v_mfma_f32_16x16x32_bf16 v[114:117], v[146:149], v[178:181], v[114:117]
	v_mfma_f32_16x16x32_bf16 v[118:121], v[154:157], v[178:181], v[118:121]
	v_mfma_f32_16x16x32_bf16 v[122:125], v[146:149], v[182:185], v[122:125]
	v_mfma_f32_16x16x32_bf16 v[126:129], v[154:157], v[182:185], v[126:129]
	v_mfma_f32_16x16x32_bf16 v[98:101], v[150:153], v[170:173], v[98:101]
	v_mfma_f32_16x16x32_bf16 v[94:97], v[158:161], v[170:173], v[94:97]
	v_mfma_f32_16x16x32_bf16 v[106:109], v[150:153], v[174:177], v[106:109]
	v_mfma_f32_16x16x32_bf16 v[110:113], v[158:161], v[174:177], v[110:113]
	v_mfma_f32_16x16x32_bf16 v[114:117], v[150:153], v[186:189], v[114:117]
	v_mfma_f32_16x16x32_bf16 v[118:121], v[158:161], v[186:189], v[118:121]
	v_mfma_f32_16x16x32_bf16 v[122:125], v[150:153], v[190:193], v[122:125]
	v_mfma_f32_16x16x32_bf16 v[126:129], v[158:161], v[190:193], v[126:129]
	s_barrier
	s_setprio 0
	s_mov_b32 m0, s29
	ds_read_b128 v[162:165], v248 offset:16384
	ds_read_b128 v[166:169], v248 offset:18432
	ds_read_b128 v[170:173], v249 offset:16384
	ds_read_b128 v[174:177], v249 offset:18432
	ds_read_b128 v[178:181], v248 offset:20480
	ds_read_b128 v[182:185], v248 offset:22528
	ds_read_b128 v[186:189], v249 offset:20480
	ds_read_b128 v[190:193], v249 offset:22528
	buffer_load_dwordx4 v233, s[8:11], s19 offen lds
	s_mov_b32 m0, s30
	s_add_i32 s21, s19, 0x40000
	buffer_load_dwordx4 v235, s[8:11], s19 offen lds
	s_mov_b32 m0, s31
	s_nop 0
	buffer_load_dwordx4 v233, s[8:11], s21 offen lds
	s_mov_b32 m0, s35
	s_nop 0
	buffer_load_dwordx4 v235, s[8:11], s21 offen lds
	s_mov_b32 m0, s28
	s_nop 0
	buffer_load_dwordx4 v1, s[8:11], s20 offen lds
	s_mov_b32 m0, s38
	s_nop 0
	buffer_load_dwordx4 v234, s[8:11], s20 offen lds
	s_waitcnt vmcnt(8)
	s_waitcnt lgkmcnt(0)
	s_setprio 1
	s_barrier
	v_mfma_f32_16x16x32_bf16 v[10:13], v[130:133], v[162:165], v[10:13]
	v_mfma_f32_16x16x32_bf16 v[6:9], v[138:141], v[162:165], v[6:9]
	v_mfma_f32_16x16x32_bf16 v[2:5], v[130:133], v[166:169], v[2:5]
	v_mfma_f32_16x16x32_bf16 v[18:21], v[138:141], v[166:169], v[18:21]
	v_mfma_f32_16x16x32_bf16 v[14:17], v[130:133], v[178:181], v[14:17]
	v_mfma_f32_16x16x32_bf16 v[26:29], v[138:141], v[178:181], v[26:29]
	v_mfma_f32_16x16x32_bf16 v[22:25], v[130:133], v[182:185], v[22:25]
	v_mfma_f32_16x16x32_bf16 v[38:41], v[138:141], v[182:185], v[38:41]
	v_mfma_f32_16x16x32_bf16 v[10:13], v[134:137], v[170:173], v[10:13]
	v_mfma_f32_16x16x32_bf16 v[6:9], v[142:145], v[170:173], v[6:9]
	v_mfma_f32_16x16x32_bf16 v[2:5], v[134:137], v[174:177], v[2:5]
	v_mfma_f32_16x16x32_bf16 v[18:21], v[142:145], v[174:177], v[18:21]
	v_mfma_f32_16x16x32_bf16 v[14:17], v[134:137], v[186:189], v[14:17]
	v_mfma_f32_16x16x32_bf16 v[26:29], v[142:145], v[186:189], v[26:29]
	v_mfma_f32_16x16x32_bf16 v[22:25], v[134:137], v[190:193], v[22:25]
	v_mfma_f32_16x16x32_bf16 v[38:41], v[142:145], v[190:193], v[38:41]
	v_mfma_f32_16x16x32_bf16 v[34:37], v[146:149], v[162:165], v[34:37]
	v_mfma_f32_16x16x32_bf16 v[30:33], v[154:157], v[162:165], v[30:33]
	v_mfma_f32_16x16x32_bf16 v[42:45], v[146:149], v[166:169], v[42:45]
	v_mfma_f32_16x16x32_bf16 v[46:49], v[154:157], v[166:169], v[46:49]
	v_mfma_f32_16x16x32_bf16 v[50:53], v[146:149], v[178:181], v[50:53]
	v_mfma_f32_16x16x32_bf16 v[54:57], v[154:157], v[178:181], v[54:57]
	v_mfma_f32_16x16x32_bf16 v[58:61], v[146:149], v[182:185], v[58:61]
	v_mfma_f32_16x16x32_bf16 v[62:65], v[154:157], v[182:185], v[62:65]
	v_mfma_f32_16x16x32_bf16 v[34:37], v[150:153], v[170:173], v[34:37]
	v_mfma_f32_16x16x32_bf16 v[30:33], v[158:161], v[170:173], v[30:33]
	v_mfma_f32_16x16x32_bf16 v[42:45], v[150:153], v[174:177], v[42:45]
	v_mfma_f32_16x16x32_bf16 v[46:49], v[158:161], v[174:177], v[46:49]
	v_mfma_f32_16x16x32_bf16 v[50:53], v[150:153], v[186:189], v[50:53]
	v_mfma_f32_16x16x32_bf16 v[54:57], v[158:161], v[186:189], v[54:57]
	v_mfma_f32_16x16x32_bf16 v[58:61], v[150:153], v[190:193], v[58:61]
	v_mfma_f32_16x16x32_bf16 v[62:65], v[158:161], v[190:193], v[62:65]
	s_barrier
	s_setprio 0
	ds_read_b128 v[130:133], v194
	ds_read_b128 v[134:137], v195
	ds_read_b128 v[138:141], v196
	ds_read_b128 v[142:145], v197
	ds_read_b128 v[146:149], v198
	ds_read_b128 v[150:153], v199
	ds_read_b128 v[154:157], v200
	ds_read_b128 v[158:161], v201
	s_add_i32 s20, s20, 0x40000
	s_mov_b32 m0, s39
	ds_read_b128 v[162:165], v248 offset:32768
	ds_read_b128 v[166:169], v248 offset:34816
	ds_read_b128 v[170:173], v249 offset:32768
	ds_read_b128 v[174:177], v249 offset:34816
	ds_read_b128 v[178:181], v248 offset:36864
	ds_read_b128 v[182:185], v248 offset:38912
	ds_read_b128 v[186:189], v249 offset:36864
	ds_read_b128 v[190:193], v249 offset:38912
	buffer_load_dwordx4 v1, s[8:11], s20 offen lds
	s_mov_b32 m0, s41
	s_nop 0
	buffer_load_dwordx4 v234, s[8:11], s20 offen lds
	s_waitcnt vmcnt(8)
	s_waitcnt lgkmcnt(0)
	s_setprio 1
	v_mfma_f32_16x16x32_bf16 v[74:77], v[130:133], v[162:165], v[74:77]
	v_mfma_f32_16x16x32_bf16 v[70:73], v[138:141], v[162:165], v[70:73]
	v_mfma_f32_16x16x32_bf16 v[66:69], v[130:133], v[166:169], v[66:69]
	v_mfma_f32_16x16x32_bf16 v[82:85], v[138:141], v[166:169], v[82:85]
	v_mfma_f32_16x16x32_bf16 v[78:81], v[130:133], v[178:181], v[78:81]
	v_mfma_f32_16x16x32_bf16 v[90:93], v[138:141], v[178:181], v[90:93]
	v_mfma_f32_16x16x32_bf16 v[86:89], v[130:133], v[182:185], v[86:89]
	v_mfma_f32_16x16x32_bf16 v[102:105], v[138:141], v[182:185], v[102:105]
	s_barrier
	v_mfma_f32_16x16x32_bf16 v[74:77], v[134:137], v[170:173], v[74:77]
	v_mfma_f32_16x16x32_bf16 v[70:73], v[142:145], v[170:173], v[70:73]
	v_mfma_f32_16x16x32_bf16 v[66:69], v[134:137], v[174:177], v[66:69]
	v_mfma_f32_16x16x32_bf16 v[82:85], v[142:145], v[174:177], v[82:85]
	v_mfma_f32_16x16x32_bf16 v[78:81], v[134:137], v[186:189], v[78:81]
	v_mfma_f32_16x16x32_bf16 v[90:93], v[142:145], v[186:189], v[90:93]
	v_mfma_f32_16x16x32_bf16 v[86:89], v[134:137], v[190:193], v[86:89]
	v_mfma_f32_16x16x32_bf16 v[102:105], v[142:145], v[190:193], v[102:105]
	v_mfma_f32_16x16x32_bf16 v[98:101], v[146:149], v[162:165], v[98:101]
	v_mfma_f32_16x16x32_bf16 v[94:97], v[154:157], v[162:165], v[94:97]
	v_mfma_f32_16x16x32_bf16 v[106:109], v[146:149], v[166:169], v[106:109]
	v_mfma_f32_16x16x32_bf16 v[110:113], v[154:157], v[166:169], v[110:113]
	v_mfma_f32_16x16x32_bf16 v[114:117], v[146:149], v[178:181], v[114:117]
	v_mfma_f32_16x16x32_bf16 v[118:121], v[154:157], v[178:181], v[118:121]
	v_mfma_f32_16x16x32_bf16 v[122:125], v[146:149], v[182:185], v[122:125]
	v_mfma_f32_16x16x32_bf16 v[126:129], v[154:157], v[182:185], v[126:129]
	v_mfma_f32_16x16x32_bf16 v[98:101], v[150:153], v[170:173], v[98:101]
	v_mfma_f32_16x16x32_bf16 v[94:97], v[158:161], v[170:173], v[94:97]
	v_mfma_f32_16x16x32_bf16 v[106:109], v[150:153], v[174:177], v[106:109]
	v_mfma_f32_16x16x32_bf16 v[110:113], v[158:161], v[174:177], v[110:113]
	v_mfma_f32_16x16x32_bf16 v[114:117], v[150:153], v[186:189], v[114:117]
	v_mfma_f32_16x16x32_bf16 v[118:121], v[158:161], v[186:189], v[118:121]
	v_mfma_f32_16x16x32_bf16 v[122:125], v[150:153], v[190:193], v[122:125]
	v_mfma_f32_16x16x32_bf16 v[126:129], v[158:161], v[190:193], v[126:129]
	s_barrier
	s_setprio 0
	s_mov_b32 m0, s44
	s_add_i32 s20, s19, 0x80
	ds_read_b128 v[162:165], v248 offset:49152
	ds_read_b128 v[166:169], v248 offset:51200
	ds_read_b128 v[170:173], v249 offset:49152
	ds_read_b128 v[174:177], v249 offset:51200
	ds_read_b128 v[178:181], v248 offset:53248
	ds_read_b128 v[182:185], v248 offset:55296
	ds_read_b128 v[186:189], v249 offset:53248
	ds_read_b128 v[190:193], v249 offset:55296
	buffer_load_dwordx4 v233, s[8:11], s20 offen lds
	s_mov_b32 m0, s45
	s_add_i32 s19, s19, 0x40080
	buffer_load_dwordx4 v235, s[8:11], s20 offen lds
	s_mov_b32 m0, s48
	s_nop 0
	buffer_load_dwordx4 v233, s[8:11], s19 offen lds
	s_mov_b32 m0, s49
	s_nop 0
	buffer_load_dwordx4 v235, s[8:11], s19 offen lds
	s_mov_b32 m0, s46
	s_nop 0
	buffer_load_dwordx4 v1, s[8:11], s18 offen lds
	s_mov_b32 m0, s47
	s_nop 0
	buffer_load_dwordx4 v234, s[8:11], s18 offen lds
	s_waitcnt vmcnt(8)
	s_waitcnt lgkmcnt(0)
	s_setprio 1
	s_barrier
	v_mfma_f32_16x16x32_bf16 v[10:13], v[130:133], v[162:165], v[10:13]
	v_mfma_f32_16x16x32_bf16 v[6:9], v[138:141], v[162:165], v[6:9]
	v_mfma_f32_16x16x32_bf16 v[2:5], v[130:133], v[166:169], v[2:5]
	v_mfma_f32_16x16x32_bf16 v[18:21], v[138:141], v[166:169], v[18:21]
	v_mfma_f32_16x16x32_bf16 v[14:17], v[130:133], v[178:181], v[14:17]
	v_mfma_f32_16x16x32_bf16 v[26:29], v[138:141], v[178:181], v[26:29]
	v_mfma_f32_16x16x32_bf16 v[22:25], v[130:133], v[182:185], v[22:25]
	v_mfma_f32_16x16x32_bf16 v[38:41], v[138:141], v[182:185], v[38:41]
	v_mfma_f32_16x16x32_bf16 v[10:13], v[134:137], v[170:173], v[10:13]
	v_mfma_f32_16x16x32_bf16 v[6:9], v[142:145], v[170:173], v[6:9]
	v_mfma_f32_16x16x32_bf16 v[2:5], v[134:137], v[174:177], v[2:5]
	v_mfma_f32_16x16x32_bf16 v[18:21], v[142:145], v[174:177], v[18:21]
	v_mfma_f32_16x16x32_bf16 v[14:17], v[134:137], v[186:189], v[14:17]
	v_mfma_f32_16x16x32_bf16 v[26:29], v[142:145], v[186:189], v[26:29]
	v_mfma_f32_16x16x32_bf16 v[22:25], v[134:137], v[190:193], v[22:25]
	v_mfma_f32_16x16x32_bf16 v[38:41], v[142:145], v[190:193], v[38:41]
	v_mfma_f32_16x16x32_bf16 v[34:37], v[146:149], v[162:165], v[34:37]
	v_mfma_f32_16x16x32_bf16 v[30:33], v[154:157], v[162:165], v[30:33]
	v_mfma_f32_16x16x32_bf16 v[42:45], v[146:149], v[166:169], v[42:45]
	v_mfma_f32_16x16x32_bf16 v[46:49], v[154:157], v[166:169], v[46:49]
	v_mfma_f32_16x16x32_bf16 v[50:53], v[146:149], v[178:181], v[50:53]
	v_mfma_f32_16x16x32_bf16 v[54:57], v[154:157], v[178:181], v[54:57]
	v_mfma_f32_16x16x32_bf16 v[58:61], v[146:149], v[182:185], v[58:61]
	v_mfma_f32_16x16x32_bf16 v[62:65], v[154:157], v[182:185], v[62:65]
	v_mfma_f32_16x16x32_bf16 v[34:37], v[150:153], v[170:173], v[34:37]
	v_mfma_f32_16x16x32_bf16 v[30:33], v[158:161], v[170:173], v[30:33]
	v_mfma_f32_16x16x32_bf16 v[42:45], v[150:153], v[174:177], v[42:45]
	v_mfma_f32_16x16x32_bf16 v[46:49], v[158:161], v[174:177], v[46:49]
	v_mfma_f32_16x16x32_bf16 v[50:53], v[150:153], v[186:189], v[50:53]
	v_mfma_f32_16x16x32_bf16 v[54:57], v[158:161], v[186:189], v[54:57]
	v_mfma_f32_16x16x32_bf16 v[58:61], v[150:153], v[190:193], v[58:61]
	v_mfma_f32_16x16x32_bf16 v[62:65], v[158:161], v[190:193], v[62:65]
	s_barrier
	s_setprio 0
	s_add_i32 s4, s4, 2
	s_addk_i32 s5, 0x100
	s_cmp_gt_u32 s4, 13
	s_cbranch_scc0 .LBB0_841
	s_and_b64 vcc, exec, s[16:17]
	s_cbranch_vccz .LBB0_844
	s_barrier

.LBB0_1122:
	ds_read_b128 v[130:133], v240
	ds_read_b128 v[134:137], v241
	ds_read_b128 v[138:141], v242
	ds_read_b128 v[142:145], v243
	ds_read_b128 v[146:149], v244
	ds_read_b128 v[150:153], v245
	ds_read_b128 v[154:157], v246
	ds_read_b128 v[158:161], v247
	s_add_i32 s8, s31, s53
	s_add_i32 s55, s26, s53
	s_add_i32 s54, s8, 0x800
	s_addk_i32 s55, 0x800
	s_cmp_eq_u32 s53, 0
	s_cselect_b32 s56, s4, s54
	s_cselect_b32 s55, s5, s55
	s_add_i32 s54, s56, 0x80
	s_add_i32 s57, s8, 0x40780
	s_mov_b32 s8, s70
	s_mov_b32 m0, s44
	ds_read_b128 v[162:165], v248
	ds_read_b128 v[166:169], v248 offset:2048
	ds_read_b128 v[170:173], v249
	ds_read_b128 v[174:177], v249 offset:2048
	ds_read_b128 v[178:181], v248 offset:4096
	ds_read_b128 v[182:185], v248 offset:6144
	ds_read_b128 v[186:189], v249 offset:4096
	ds_read_b128 v[190:193], v249 offset:6144
	buffer_load_dwordx4 v1, s[8:11], s57 offen lds
	s_mov_b32 m0, s45
	s_nop 0
	buffer_load_dwordx4 v234, s[8:11], s57 offen lds
	s_waitcnt vmcnt(8)
	s_waitcnt lgkmcnt(0)
	s_setprio 1
	v_mfma_f32_16x16x32_bf16 v[126:129], v[130:133], v[162:165], v[126:129]
	v_mfma_f32_16x16x32_bf16 v[122:125], v[138:141], v[162:165], v[122:125]
	v_mfma_f32_16x16x32_bf16 v[118:121], v[130:133], v[166:169], v[118:121]
	v_mfma_f32_16x16x32_bf16 v[114:117], v[138:141], v[166:169], v[114:117]
	v_mfma_f32_16x16x32_bf16 v[110:113], v[130:133], v[178:181], v[110:113]
	v_mfma_f32_16x16x32_bf16 v[106:109], v[138:141], v[178:181], v[106:109]
	v_mfma_f32_16x16x32_bf16 v[102:105], v[130:133], v[182:185], v[102:105]
	v_mfma_f32_16x16x32_bf16 v[98:101], v[138:141], v[182:185], v[98:101]
	s_barrier
	v_mfma_f32_16x16x32_bf16 v[126:129], v[134:137], v[170:173], v[126:129]
	v_mfma_f32_16x16x32_bf16 v[122:125], v[142:145], v[170:173], v[122:125]
	v_mfma_f32_16x16x32_bf16 v[118:121], v[134:137], v[174:177], v[118:121]
	v_mfma_f32_16x16x32_bf16 v[114:117], v[142:145], v[174:177], v[114:117]
	v_mfma_f32_16x16x32_bf16 v[110:113], v[134:137], v[186:189], v[110:113]
	v_mfma_f32_16x16x32_bf16 v[106:109], v[142:145], v[186:189], v[106:109]
	v_mfma_f32_16x16x32_bf16 v[102:105], v[134:137], v[190:193], v[102:105]
	v_mfma_f32_16x16x32_bf16 v[98:101], v[142:145], v[190:193], v[98:101]
	v_mfma_f32_16x16x32_bf16 v[94:97], v[146:149], v[162:165], v[94:97]
	v_mfma_f32_16x16x32_bf16 v[90:93], v[154:157], v[162:165], v[90:93]
	v_mfma_f32_16x16x32_bf16 v[86:89], v[146:149], v[166:169], v[86:89]
	v_mfma_f32_16x16x32_bf16 v[82:85], v[154:157], v[166:169], v[82:85]
	v_mfma_f32_16x16x32_bf16 v[78:81], v[146:149], v[178:181], v[78:81]
	v_mfma_f32_16x16x32_bf16 v[74:77], v[154:157], v[178:181], v[74:77]
	v_mfma_f32_16x16x32_bf16 v[70:73], v[146:149], v[182:185], v[70:73]
	v_mfma_f32_16x16x32_bf16 v[66:69], v[154:157], v[182:185], v[66:69]
	v_mfma_f32_16x16x32_bf16 v[94:97], v[150:153], v[170:173], v[94:97]
	v_mfma_f32_16x16x32_bf16 v[90:93], v[158:161], v[170:173], v[90:93]
	v_mfma_f32_16x16x32_bf16 v[86:89], v[150:153], v[174:177], v[86:89]
	v_mfma_f32_16x16x32_bf16 v[82:85], v[158:161], v[174:177], v[82:85]
	v_mfma_f32_16x16x32_bf16 v[78:81], v[150:153], v[186:189], v[78:81]
	v_mfma_f32_16x16x32_bf16 v[74:77], v[158:161], v[186:189], v[74:77]
	v_mfma_f32_16x16x32_bf16 v[70:73], v[150:153], v[190:193], v[70:73]
	v_mfma_f32_16x16x32_bf16 v[66:69], v[158:161], v[190:193], v[66:69]
	s_barrier
	s_setprio 0
	s_mov_b32 m0, s23
	ds_read_b128 v[162:165], v248 offset:16384
	ds_read_b128 v[166:169], v248 offset:18432
	ds_read_b128 v[170:173], v249 offset:16384
	ds_read_b128 v[174:177], v249 offset:18432
	ds_read_b128 v[178:181], v248 offset:20480
	ds_read_b128 v[182:185], v248 offset:22528
	ds_read_b128 v[186:189], v249 offset:20480
	ds_read_b128 v[190:193], v249 offset:22528
	buffer_load_dwordx4 v233, s[8:11], s55 offen lds
	s_mov_b32 m0, s24
	s_add_i32 s57, s55, 0x40000
	buffer_load_dwordx4 v235, s[8:11], s55 offen lds
	s_mov_b32 m0, s25
	s_nop 0
	buffer_load_dwordx4 v233, s[8:11], s57 offen lds
	s_mov_b32 m0, s27
	s_nop 0
	buffer_load_dwordx4 v235, s[8:11], s57 offen lds
	s_mov_b32 m0, s22
	s_nop 0
	buffer_load_dwordx4 v1, s[8:11], s56 offen lds
	s_mov_b32 m0, s28
	s_nop 0
	buffer_load_dwordx4 v234, s[8:11], s56 offen lds
	s_waitcnt vmcnt(8)
	s_waitcnt lgkmcnt(0)
	s_setprio 1
	s_barrier
	v_mfma_f32_16x16x32_bf16 v[62:65], v[130:133], v[162:165], v[62:65]
	v_mfma_f32_16x16x32_bf16 v[58:61], v[138:141], v[162:165], v[58:61]
	v_mfma_f32_16x16x32_bf16 v[54:57], v[130:133], v[166:169], v[54:57]
	v_mfma_f32_16x16x32_bf16 v[50:53], v[138:141], v[166:169], v[50:53]
	v_mfma_f32_16x16x32_bf16 v[46:49], v[130:133], v[178:181], v[46:49]
	v_mfma_f32_16x16x32_bf16 v[42:45], v[138:141], v[178:181], v[42:45]
	v_mfma_f32_16x16x32_bf16 v[38:41], v[130:133], v[182:185], v[38:41]
	v_mfma_f32_16x16x32_bf16 v[34:37], v[138:141], v[182:185], v[34:37]
	v_mfma_f32_16x16x32_bf16 v[62:65], v[134:137], v[170:173], v[62:65]
	v_mfma_f32_16x16x32_bf16 v[58:61], v[142:145], v[170:173], v[58:61]
	v_mfma_f32_16x16x32_bf16 v[54:57], v[134:137], v[174:177], v[54:57]
	v_mfma_f32_16x16x32_bf16 v[50:53], v[142:145], v[174:177], v[50:53]
	v_mfma_f32_16x16x32_bf16 v[46:49], v[134:137], v[186:189], v[46:49]
	v_mfma_f32_16x16x32_bf16 v[42:45], v[142:145], v[186:189], v[42:45]
	v_mfma_f32_16x16x32_bf16 v[38:41], v[134:137], v[190:193], v[38:41]
	v_mfma_f32_16x16x32_bf16 v[34:37], v[142:145], v[190:193], v[34:37]
	v_mfma_f32_16x16x32_bf16 v[30:33], v[146:149], v[162:165], v[30:33]
	v_mfma_f32_16x16x32_bf16 v[26:29], v[154:157], v[162:165], v[26:29]
	v_mfma_f32_16x16x32_bf16 v[22:25], v[146:149], v[166:169], v[22:25]
	v_mfma_f32_16x16x32_bf16 v[18:21], v[154:157], v[166:169], v[18:21]
	v_mfma_f32_16x16x32_bf16 v[14:17], v[146:149], v[178:181], v[14:17]
	v_mfma_f32_16x16x32_bf16 v[10:13], v[154:157], v[178:181], v[10:13]
	v_mfma_f32_16x16x32_bf16 v[6:9], v[146:149], v[182:185], v[6:9]
	v_mfma_f32_16x16x32_bf16 v[2:5], v[154:157], v[182:185], v[2:5]
	v_mfma_f32_16x16x32_bf16 v[30:33], v[150:153], v[170:173], v[30:33]
	v_mfma_f32_16x16x32_bf16 v[26:29], v[158:161], v[170:173], v[26:29]
	v_mfma_f32_16x16x32_bf16 v[22:25], v[150:153], v[174:177], v[22:25]
	v_mfma_f32_16x16x32_bf16 v[18:21], v[158:161], v[174:177], v[18:21]
	v_mfma_f32_16x16x32_bf16 v[14:17], v[150:153], v[186:189], v[14:17]
	v_mfma_f32_16x16x32_bf16 v[10:13], v[158:161], v[186:189], v[10:13]
	v_mfma_f32_16x16x32_bf16 v[6:9], v[150:153], v[190:193], v[6:9]
	v_mfma_f32_16x16x32_bf16 v[2:5], v[158:161], v[190:193], v[2:5]
	s_barrier
	s_setprio 0
	ds_read_b128 v[130:133], v194
	ds_read_b128 v[134:137], v195
	ds_read_b128 v[138:141], v196
	ds_read_b128 v[142:145], v197
	ds_read_b128 v[146:149], v198
	ds_read_b128 v[150:153], v199
	ds_read_b128 v[154:157], v200
	ds_read_b128 v[158:161], v201
	s_add_i32 s56, s56, 0x40000
	s_mov_b32 m0, s29
	ds_read_b128 v[162:165], v248 offset:32768
	ds_read_b128 v[166:169], v248 offset:34816
	ds_read_b128 v[170:173], v249 offset:32768
	ds_read_b128 v[174:177], v249 offset:34816
	ds_read_b128 v[178:181], v248 offset:36864
	ds_read_b128 v[182:185], v248 offset:38912
	ds_read_b128 v[186:189], v249 offset:36864
	ds_read_b128 v[190:193], v249 offset:38912
	buffer_load_dwordx4 v1, s[8:11], s56 offen lds
	s_mov_b32 m0, s30
	s_nop 0
	buffer_load_dwordx4 v234, s[8:11], s56 offen lds
	s_waitcnt vmcnt(8)
	s_waitcnt lgkmcnt(0)
	s_setprio 1
	v_mfma_f32_16x16x32_bf16 v[126:129], v[130:133], v[162:165], v[126:129]
	v_mfma_f32_16x16x32_bf16 v[122:125], v[138:141], v[162:165], v[122:125]
	v_mfma_f32_16x16x32_bf16 v[118:121], v[130:133], v[166:169], v[118:121]
	v_mfma_f32_16x16x32_bf16 v[114:117], v[138:141], v[166:169], v[114:117]
	v_mfma_f32_16x16x32_bf16 v[110:113], v[130:133], v[178:181], v[110:113]
	v_mfma_f32_16x16x32_bf16 v[106:109], v[138:141], v[178:181], v[106:109]
	v_mfma_f32_16x16x32_bf16 v[102:105], v[130:133], v[182:185], v[102:105]
	v_mfma_f32_16x16x32_bf16 v[98:101], v[138:141], v[182:185], v[98:101]
	s_barrier
	v_mfma_f32_16x16x32_bf16 v[126:129], v[134:137], v[170:173], v[126:129]
	v_mfma_f32_16x16x32_bf16 v[122:125], v[142:145], v[170:173], v[122:125]
	v_mfma_f32_16x16x32_bf16 v[118:121], v[134:137], v[174:177], v[118:121]
	v_mfma_f32_16x16x32_bf16 v[114:117], v[142:145], v[174:177], v[114:117]
	v_mfma_f32_16x16x32_bf16 v[110:113], v[134:137], v[186:189], v[110:113]
	v_mfma_f32_16x16x32_bf16 v[106:109], v[142:145], v[186:189], v[106:109]
	v_mfma_f32_16x16x32_bf16 v[102:105], v[134:137], v[190:193], v[102:105]
	v_mfma_f32_16x16x32_bf16 v[98:101], v[142:145], v[190:193], v[98:101]
	v_mfma_f32_16x16x32_bf16 v[94:97], v[146:149], v[162:165], v[94:97]
	v_mfma_f32_16x16x32_bf16 v[90:93], v[154:157], v[162:165], v[90:93]
	v_mfma_f32_16x16x32_bf16 v[86:89], v[146:149], v[166:169], v[86:89]
	v_mfma_f32_16x16x32_bf16 v[82:85], v[154:157], v[166:169], v[82:85]
	v_mfma_f32_16x16x32_bf16 v[78:81], v[146:149], v[178:181], v[78:81]
	v_mfma_f32_16x16x32_bf16 v[74:77], v[154:157], v[178:181], v[74:77]
	v_mfma_f32_16x16x32_bf16 v[70:73], v[146:149], v[182:185], v[70:73]
	v_mfma_f32_16x16x32_bf16 v[66:69], v[154:157], v[182:185], v[66:69]
	v_mfma_f32_16x16x32_bf16 v[94:97], v[150:153], v[170:173], v[94:97]
	v_mfma_f32_16x16x32_bf16 v[90:93], v[158:161], v[170:173], v[90:93]
	v_mfma_f32_16x16x32_bf16 v[86:89], v[150:153], v[174:177], v[86:89]
	v_mfma_f32_16x16x32_bf16 v[82:85], v[158:161], v[174:177], v[82:85]
	v_mfma_f32_16x16x32_bf16 v[78:81], v[150:153], v[186:189], v[78:81]
	v_mfma_f32_16x16x32_bf16 v[74:77], v[158:161], v[186:189], v[74:77]
	v_mfma_f32_16x16x32_bf16 v[70:73], v[150:153], v[190:193], v[70:73]
	v_mfma_f32_16x16x32_bf16 v[66:69], v[158:161], v[190:193], v[66:69]
	s_barrier
	s_setprio 0
	s_mov_b32 m0, s35
	s_add_i32 s56, s55, 0x80
	ds_read_b128 v[162:165], v248 offset:49152
	ds_read_b128 v[166:169], v248 offset:51200
	ds_read_b128 v[170:173], v249 offset:49152
	ds_read_b128 v[174:177], v249 offset:51200
	ds_read_b128 v[178:181], v248 offset:53248
	ds_read_b128 v[182:185], v248 offset:55296
	ds_read_b128 v[186:189], v249 offset:53248
	ds_read_b128 v[190:193], v249 offset:55296
	buffer_load_dwordx4 v233, s[8:11], s56 offen lds
	s_mov_b32 m0, s36
	s_add_i32 s55, s55, 0x40080
	buffer_load_dwordx4 v235, s[8:11], s56 offen lds
	s_mov_b32 m0, s39
	s_nop 0
	buffer_load_dwordx4 v233, s[8:11], s55 offen lds
	s_mov_b32 m0, s41
	s_nop 0
	buffer_load_dwordx4 v235, s[8:11], s55 offen lds
	s_mov_b32 m0, s37
	s_nop 0
	buffer_load_dwordx4 v1, s[8:11], s54 offen lds
	s_mov_b32 m0, s38
	s_nop 0
	buffer_load_dwordx4 v234, s[8:11], s54 offen lds
	s_waitcnt vmcnt(8)
	s_waitcnt lgkmcnt(0)
	s_setprio 1
	s_barrier
	v_mfma_f32_16x16x32_bf16 v[62:65], v[130:133], v[162:165], v[62:65]
	v_mfma_f32_16x16x32_bf16 v[58:61], v[138:141], v[162:165], v[58:61]
	v_mfma_f32_16x16x32_bf16 v[54:57], v[130:133], v[166:169], v[54:57]
	v_mfma_f32_16x16x32_bf16 v[50:53], v[138:141], v[166:169], v[50:53]
	v_mfma_f32_16x16x32_bf16 v[46:49], v[130:133], v[178:181], v[46:49]
	v_mfma_f32_16x16x32_bf16 v[42:45], v[138:141], v[178:181], v[42:45]
	v_mfma_f32_16x16x32_bf16 v[38:41], v[130:133], v[182:185], v[38:41]
	v_mfma_f32_16x16x32_bf16 v[34:37], v[138:141], v[182:185], v[34:37]
	v_mfma_f32_16x16x32_bf16 v[62:65], v[134:137], v[170:173], v[62:65]
	v_mfma_f32_16x16x32_bf16 v[58:61], v[142:145], v[170:173], v[58:61]
	v_mfma_f32_16x16x32_bf16 v[54:57], v[134:137], v[174:177], v[54:57]
	v_mfma_f32_16x16x32_bf16 v[50:53], v[142:145], v[174:177], v[50:53]
	v_mfma_f32_16x16x32_bf16 v[46:49], v[134:137], v[186:189], v[46:49]
	v_mfma_f32_16x16x32_bf16 v[42:45], v[142:145], v[186:189], v[42:45]
	v_mfma_f32_16x16x32_bf16 v[38:41], v[134:137], v[190:193], v[38:41]
	v_mfma_f32_16x16x32_bf16 v[34:37], v[142:145], v[190:193], v[34:37]
	v_mfma_f32_16x16x32_bf16 v[30:33], v[146:149], v[162:165], v[30:33]
	v_mfma_f32_16x16x32_bf16 v[26:29], v[154:157], v[162:165], v[26:29]
	v_mfma_f32_16x16x32_bf16 v[22:25], v[146:149], v[166:169], v[22:25]
	v_mfma_f32_16x16x32_bf16 v[18:21], v[154:157], v[166:169], v[18:21]
	v_mfma_f32_16x16x32_bf16 v[14:17], v[146:149], v[178:181], v[14:17]
	v_mfma_f32_16x16x32_bf16 v[10:13], v[154:157], v[178:181], v[10:13]
	v_mfma_f32_16x16x32_bf16 v[6:9], v[146:149], v[182:185], v[6:9]
	v_mfma_f32_16x16x32_bf16 v[2:5], v[154:157], v[182:185], v[2:5]
	v_mfma_f32_16x16x32_bf16 v[30:33], v[150:153], v[170:173], v[30:33]
	v_mfma_f32_16x16x32_bf16 v[26:29], v[158:161], v[170:173], v[26:29]
	v_mfma_f32_16x16x32_bf16 v[22:25], v[150:153], v[174:177], v[22:25]
	v_mfma_f32_16x16x32_bf16 v[18:21], v[158:161], v[174:177], v[18:21]
	v_mfma_f32_16x16x32_bf16 v[14:17], v[150:153], v[186:189], v[14:17]
	v_mfma_f32_16x16x32_bf16 v[10:13], v[158:161], v[186:189], v[10:13]
	v_mfma_f32_16x16x32_bf16 v[6:9], v[150:153], v[190:193], v[6:9]
	v_mfma_f32_16x16x32_bf16 v[2:5], v[158:161], v[190:193], v[2:5]
	s_barrier
	s_setprio 0
	s_add_i32 s33, s33, 2
	s_addk_i32 s53, 0x100
	s_cmp_gt_u32 s33, 13
	s_cbranch_scc0 .LBB0_1122
	s_and_b64 vcc, exec, s[16:17]
	s_cbranch_vccz .LBB0_1125
	s_barrier

.LBB0_1251:
	ds_read_b128 v[130:133], v239
	ds_read_b128 v[134:137], v240
	ds_read_b128 v[138:141], v241
	ds_read_b128 v[142:145], v242
	ds_read_b128 v[146:149], v243
	ds_read_b128 v[150:153], v244
	ds_read_b128 v[154:157], v245
	ds_read_b128 v[158:161], v246
	s_add_i32 s8, s51, s5
	s_add_i32 s31, s46, s5
	s_add_i32 s30, s8, 0x2000
	s_addk_i32 s31, 0x2000
	s_cmp_eq_u32 s5, 0
	s_cselect_b32 s33, s0, s30
	s_cselect_b32 s31, s1, s31
	s_add_i32 s30, s33, 0x80
	s_add_i32 s34, s8, 0x101f80
	s_mov_b32 s8, s70
	s_mov_b32 m0, s61
	ds_read_b128 v[162:165], v247
	ds_read_b128 v[166:169], v247 offset:2048
	ds_read_b128 v[170:173], v248
	ds_read_b128 v[174:177], v248 offset:2048
	ds_read_b128 v[178:181], v247 offset:4096
	ds_read_b128 v[182:185], v247 offset:6144
	ds_read_b128 v[186:189], v248 offset:4096
	ds_read_b128 v[190:193], v248 offset:6144
	buffer_load_dwordx4 v230, s[8:11], s34 offen lds
	s_mov_b32 m0, s64
	s_nop 0
	buffer_load_dwordx4 v233, s[8:11], s34 offen lds
	s_waitcnt vmcnt(8)
	s_waitcnt lgkmcnt(0)
	s_setprio 1
	v_mfma_f32_16x16x32_bf16 v[74:77], v[130:133], v[162:165], v[74:77]
	v_mfma_f32_16x16x32_bf16 v[70:73], v[138:141], v[162:165], v[70:73]
	v_mfma_f32_16x16x32_bf16 v[66:69], v[130:133], v[166:169], v[66:69]
	v_mfma_f32_16x16x32_bf16 v[82:85], v[138:141], v[166:169], v[82:85]
	v_mfma_f32_16x16x32_bf16 v[78:81], v[130:133], v[178:181], v[78:81]
	v_mfma_f32_16x16x32_bf16 v[90:93], v[138:141], v[178:181], v[90:93]
	v_mfma_f32_16x16x32_bf16 v[86:89], v[130:133], v[182:185], v[86:89]
	v_mfma_f32_16x16x32_bf16 v[102:105], v[138:141], v[182:185], v[102:105]
	s_barrier
	v_mfma_f32_16x16x32_bf16 v[74:77], v[134:137], v[170:173], v[74:77]
	v_mfma_f32_16x16x32_bf16 v[70:73], v[142:145], v[170:173], v[70:73]
	v_mfma_f32_16x16x32_bf16 v[66:69], v[134:137], v[174:177], v[66:69]
	v_mfma_f32_16x16x32_bf16 v[82:85], v[142:145], v[174:177], v[82:85]
	v_mfma_f32_16x16x32_bf16 v[78:81], v[134:137], v[186:189], v[78:81]
	v_mfma_f32_16x16x32_bf16 v[90:93], v[142:145], v[186:189], v[90:93]
	v_mfma_f32_16x16x32_bf16 v[86:89], v[134:137], v[190:193], v[86:89]
	v_mfma_f32_16x16x32_bf16 v[102:105], v[142:145], v[190:193], v[102:105]
	v_mfma_f32_16x16x32_bf16 v[98:101], v[146:149], v[162:165], v[98:101]
	v_mfma_f32_16x16x32_bf16 v[94:97], v[154:157], v[162:165], v[94:97]
	v_mfma_f32_16x16x32_bf16 v[106:109], v[146:149], v[166:169], v[106:109]
	v_mfma_f32_16x16x32_bf16 v[110:113], v[154:157], v[166:169], v[110:113]
	v_mfma_f32_16x16x32_bf16 v[114:117], v[146:149], v[178:181], v[114:117]
	v_mfma_f32_16x16x32_bf16 v[118:121], v[154:157], v[178:181], v[118:121]
	v_mfma_f32_16x16x32_bf16 v[122:125], v[146:149], v[182:185], v[122:125]
	v_mfma_f32_16x16x32_bf16 v[126:129], v[154:157], v[182:185], v[126:129]
	v_mfma_f32_16x16x32_bf16 v[98:101], v[150:153], v[170:173], v[98:101]
	v_mfma_f32_16x16x32_bf16 v[94:97], v[158:161], v[170:173], v[94:97]
	v_mfma_f32_16x16x32_bf16 v[106:109], v[150:153], v[174:177], v[106:109]
	v_mfma_f32_16x16x32_bf16 v[110:113], v[158:161], v[174:177], v[110:113]
	v_mfma_f32_16x16x32_bf16 v[114:117], v[150:153], v[186:189], v[114:117]
	v_mfma_f32_16x16x32_bf16 v[118:121], v[158:161], v[186:189], v[118:121]
	v_mfma_f32_16x16x32_bf16 v[122:125], v[150:153], v[190:193], v[122:125]
	v_mfma_f32_16x16x32_bf16 v[126:129], v[158:161], v[190:193], v[126:129]
	s_barrier
	s_setprio 0
	s_mov_b32 m0, s43
	ds_read_b128 v[162:165], v247 offset:16384
	ds_read_b128 v[166:169], v247 offset:18432
	ds_read_b128 v[170:173], v248 offset:16384
	ds_read_b128 v[174:177], v248 offset:18432
	ds_read_b128 v[178:181], v247 offset:20480
	ds_read_b128 v[182:185], v247 offset:22528
	ds_read_b128 v[186:189], v248 offset:20480
	ds_read_b128 v[190:193], v248 offset:22528
	buffer_load_dwordx4 v231, s[8:11], s31 offen lds
	s_mov_b32 m0, s44
	s_add_i32 s34, s31, 0x100000
	buffer_load_dwordx4 v234, s[8:11], s31 offen lds
	s_mov_b32 m0, s45
	s_nop 0
	buffer_load_dwordx4 v231, s[8:11], s34 offen lds
	s_mov_b32 m0, s47
	s_nop 0
	buffer_load_dwordx4 v234, s[8:11], s34 offen lds
	s_mov_b32 m0, s42
	s_nop 0
	buffer_load_dwordx4 v230, s[8:11], s33 offen lds
	s_mov_b32 m0, s48
	s_nop 0
	buffer_load_dwordx4 v233, s[8:11], s33 offen lds
	s_waitcnt vmcnt(8)
	s_waitcnt lgkmcnt(0)
	s_setprio 1
	s_barrier
	v_mfma_f32_16x16x32_bf16 v[10:13], v[130:133], v[162:165], v[10:13]
	v_mfma_f32_16x16x32_bf16 v[6:9], v[138:141], v[162:165], v[6:9]
	v_mfma_f32_16x16x32_bf16 v[0:3], v[130:133], v[166:169], v[2:5]
	v_mfma_f32_16x16x32_bf16 v[18:21], v[138:141], v[166:169], v[18:21]
	v_mfma_f32_16x16x32_bf16 v[14:17], v[130:133], v[178:181], v[14:17]
	v_mfma_f32_16x16x32_bf16 v[26:29], v[138:141], v[178:181], v[26:29]
	v_mfma_f32_16x16x32_bf16 v[22:25], v[130:133], v[182:185], v[22:25]
	v_mfma_f32_16x16x32_bf16 v[38:41], v[138:141], v[182:185], v[38:41]
	v_mfma_f32_16x16x32_bf16 v[10:13], v[134:137], v[170:173], v[10:13]
	v_mfma_f32_16x16x32_bf16 v[6:9], v[142:145], v[170:173], v[6:9]
	v_mfma_f32_16x16x32_bf16 v[0:3], v[134:137], v[174:177], v[0:3]
	v_mfma_f32_16x16x32_bf16 v[18:21], v[142:145], v[174:177], v[18:21]
	v_mfma_f32_16x16x32_bf16 v[14:17], v[134:137], v[186:189], v[14:17]
	v_mfma_f32_16x16x32_bf16 v[26:29], v[142:145], v[186:189], v[26:29]
	v_mfma_f32_16x16x32_bf16 v[22:25], v[134:137], v[190:193], v[22:25]
	v_mfma_f32_16x16x32_bf16 v[38:41], v[142:145], v[190:193], v[38:41]
	v_mfma_f32_16x16x32_bf16 v[34:37], v[146:149], v[162:165], v[34:37]
	v_mfma_f32_16x16x32_bf16 v[30:33], v[154:157], v[162:165], v[30:33]
	v_mfma_f32_16x16x32_bf16 v[42:45], v[146:149], v[166:169], v[42:45]
	v_mfma_f32_16x16x32_bf16 v[46:49], v[154:157], v[166:169], v[46:49]
	v_mfma_f32_16x16x32_bf16 v[50:53], v[146:149], v[178:181], v[50:53]
	v_mfma_f32_16x16x32_bf16 v[54:57], v[154:157], v[178:181], v[54:57]
	v_mfma_f32_16x16x32_bf16 v[58:61], v[146:149], v[182:185], v[58:61]
	v_mfma_f32_16x16x32_bf16 v[62:65], v[154:157], v[182:185], v[62:65]
	v_mfma_f32_16x16x32_bf16 v[34:37], v[150:153], v[170:173], v[34:37]
	v_mfma_f32_16x16x32_bf16 v[30:33], v[158:161], v[170:173], v[30:33]
	v_mfma_f32_16x16x32_bf16 v[42:45], v[150:153], v[174:177], v[42:45]
	v_mfma_f32_16x16x32_bf16 v[46:49], v[158:161], v[174:177], v[46:49]
	v_mfma_f32_16x16x32_bf16 v[50:53], v[150:153], v[186:189], v[50:53]
	v_mfma_f32_16x16x32_bf16 v[54:57], v[158:161], v[186:189], v[54:57]
	v_mfma_f32_16x16x32_bf16 v[58:61], v[150:153], v[190:193], v[58:61]
	v_mfma_f32_16x16x32_bf16 v[62:65], v[158:161], v[190:193], v[62:65]
	s_barrier
	s_setprio 0
	ds_read_b128 v[130:133], v194
	ds_read_b128 v[134:137], v195
	ds_read_b128 v[138:141], v196
	ds_read_b128 v[142:145], v197
	ds_read_b128 v[146:149], v198
	ds_read_b128 v[150:153], v199
	ds_read_b128 v[154:157], v200
	ds_read_b128 v[158:161], v201
	s_add_i32 s33, s33, 0x100000
	s_mov_b32 m0, s49
	ds_read_b128 v[162:165], v247 offset:32768
	ds_read_b128 v[166:169], v247 offset:34816
	ds_read_b128 v[170:173], v248 offset:32768
	ds_read_b128 v[174:177], v248 offset:34816
	ds_read_b128 v[178:181], v247 offset:36864
	ds_read_b128 v[182:185], v247 offset:38912
	ds_read_b128 v[186:189], v248 offset:36864
	ds_read_b128 v[190:193], v248 offset:38912
	buffer_load_dwordx4 v230, s[8:11], s33 offen lds
	s_mov_b32 m0, s50
	s_nop 0
	buffer_load_dwordx4 v233, s[8:11], s33 offen lds
	s_waitcnt vmcnt(8)
	s_waitcnt lgkmcnt(0)
	s_setprio 1
	v_mfma_f32_16x16x32_bf16 v[74:77], v[130:133], v[162:165], v[74:77]
	v_mfma_f32_16x16x32_bf16 v[70:73], v[138:141], v[162:165], v[70:73]
	v_mfma_f32_16x16x32_bf16 v[66:69], v[130:133], v[166:169], v[66:69]
	v_mfma_f32_16x16x32_bf16 v[82:85], v[138:141], v[166:169], v[82:85]
	v_mfma_f32_16x16x32_bf16 v[78:81], v[130:133], v[178:181], v[78:81]
	v_mfma_f32_16x16x32_bf16 v[90:93], v[138:141], v[178:181], v[90:93]
	v_mfma_f32_16x16x32_bf16 v[86:89], v[130:133], v[182:185], v[86:89]
	v_mfma_f32_16x16x32_bf16 v[102:105], v[138:141], v[182:185], v[102:105]
	s_barrier
	v_mfma_f32_16x16x32_bf16 v[74:77], v[134:137], v[170:173], v[74:77]
	v_mfma_f32_16x16x32_bf16 v[70:73], v[142:145], v[170:173], v[70:73]
	v_mfma_f32_16x16x32_bf16 v[66:69], v[134:137], v[174:177], v[66:69]
	v_mfma_f32_16x16x32_bf16 v[82:85], v[142:145], v[174:177], v[82:85]
	v_mfma_f32_16x16x32_bf16 v[78:81], v[134:137], v[186:189], v[78:81]
	v_mfma_f32_16x16x32_bf16 v[90:93], v[142:145], v[186:189], v[90:93]
	v_mfma_f32_16x16x32_bf16 v[86:89], v[134:137], v[190:193], v[86:89]
	v_mfma_f32_16x16x32_bf16 v[102:105], v[142:145], v[190:193], v[102:105]
	v_mfma_f32_16x16x32_bf16 v[98:101], v[146:149], v[162:165], v[98:101]
	v_mfma_f32_16x16x32_bf16 v[94:97], v[154:157], v[162:165], v[94:97]
	v_mfma_f32_16x16x32_bf16 v[106:109], v[146:149], v[166:169], v[106:109]
	v_mfma_f32_16x16x32_bf16 v[110:113], v[154:157], v[166:169], v[110:113]
	v_mfma_f32_16x16x32_bf16 v[114:117], v[146:149], v[178:181], v[114:117]
	v_mfma_f32_16x16x32_bf16 v[118:121], v[154:157], v[178:181], v[118:121]
	v_mfma_f32_16x16x32_bf16 v[122:125], v[146:149], v[182:185], v[122:125]
	v_mfma_f32_16x16x32_bf16 v[126:129], v[154:157], v[182:185], v[126:129]
	v_mfma_f32_16x16x32_bf16 v[98:101], v[150:153], v[170:173], v[98:101]
	v_mfma_f32_16x16x32_bf16 v[94:97], v[158:161], v[170:173], v[94:97]
	v_mfma_f32_16x16x32_bf16 v[106:109], v[150:153], v[174:177], v[106:109]
	v_mfma_f32_16x16x32_bf16 v[110:113], v[158:161], v[174:177], v[110:113]
	v_mfma_f32_16x16x32_bf16 v[114:117], v[150:153], v[186:189], v[114:117]
	v_mfma_f32_16x16x32_bf16 v[118:121], v[158:161], v[186:189], v[118:121]
	v_mfma_f32_16x16x32_bf16 v[122:125], v[150:153], v[190:193], v[122:125]
	v_mfma_f32_16x16x32_bf16 v[126:129], v[158:161], v[190:193], v[126:129]
	s_barrier
	s_setprio 0
	s_mov_b32 m0, s53
	s_add_i32 s33, s31, 0x80
	ds_read_b128 v[162:165], v247 offset:49152
	ds_read_b128 v[166:169], v247 offset:51200
	ds_read_b128 v[170:173], v248 offset:49152
	ds_read_b128 v[174:177], v248 offset:51200
	ds_read_b128 v[178:181], v247 offset:53248
	ds_read_b128 v[182:185], v247 offset:55296
	ds_read_b128 v[186:189], v248 offset:53248
	ds_read_b128 v[190:193], v248 offset:55296
	buffer_load_dwordx4 v231, s[8:11], s33 offen lds
	s_mov_b32 m0, s54
	s_add_i32 s31, s31, 0x100080
	buffer_load_dwordx4 v234, s[8:11], s33 offen lds
	s_mov_b32 m0, s57
	s_nop 0
	buffer_load_dwordx4 v231, s[8:11], s31 offen lds
	s_mov_b32 m0, s58
	s_nop 0
	buffer_load_dwordx4 v234, s[8:11], s31 offen lds
	s_mov_b32 m0, s55
	s_nop 0
	buffer_load_dwordx4 v230, s[8:11], s30 offen lds
	s_mov_b32 m0, s56
	s_nop 0
	buffer_load_dwordx4 v233, s[8:11], s30 offen lds
	s_waitcnt vmcnt(8)
	s_waitcnt lgkmcnt(0)
	s_setprio 1
	s_barrier
	v_mfma_f32_16x16x32_bf16 v[10:13], v[130:133], v[162:165], v[10:13]
	v_mfma_f32_16x16x32_bf16 v[4:7], v[138:141], v[162:165], v[6:9]
	v_mfma_f32_16x16x32_bf16 v[0:3], v[130:133], v[166:169], v[0:3]
	v_mfma_f32_16x16x32_bf16 v[18:21], v[138:141], v[166:169], v[18:21]
	v_mfma_f32_16x16x32_bf16 v[14:17], v[130:133], v[178:181], v[14:17]
	v_mfma_f32_16x16x32_bf16 v[26:29], v[138:141], v[178:181], v[26:29]
	v_mfma_f32_16x16x32_bf16 v[22:25], v[130:133], v[182:185], v[22:25]
	v_mfma_f32_16x16x32_bf16 v[38:41], v[138:141], v[182:185], v[38:41]
	v_mfma_f32_16x16x32_bf16 v[10:13], v[134:137], v[170:173], v[10:13]
	v_mfma_f32_16x16x32_bf16 v[6:9], v[142:145], v[170:173], v[4:7]
	v_mfma_f32_16x16x32_bf16 v[2:5], v[134:137], v[174:177], v[0:3]
	v_mfma_f32_16x16x32_bf16 v[18:21], v[142:145], v[174:177], v[18:21]
	v_mfma_f32_16x16x32_bf16 v[14:17], v[134:137], v[186:189], v[14:17]
	v_mfma_f32_16x16x32_bf16 v[26:29], v[142:145], v[186:189], v[26:29]
	v_mfma_f32_16x16x32_bf16 v[22:25], v[134:137], v[190:193], v[22:25]
	v_mfma_f32_16x16x32_bf16 v[38:41], v[142:145], v[190:193], v[38:41]
	v_mfma_f32_16x16x32_bf16 v[34:37], v[146:149], v[162:165], v[34:37]
	v_mfma_f32_16x16x32_bf16 v[30:33], v[154:157], v[162:165], v[30:33]
	v_mfma_f32_16x16x32_bf16 v[42:45], v[146:149], v[166:169], v[42:45]
	v_mfma_f32_16x16x32_bf16 v[46:49], v[154:157], v[166:169], v[46:49]
	v_mfma_f32_16x16x32_bf16 v[50:53], v[146:149], v[178:181], v[50:53]
	v_mfma_f32_16x16x32_bf16 v[54:57], v[154:157], v[178:181], v[54:57]
	v_mfma_f32_16x16x32_bf16 v[58:61], v[146:149], v[182:185], v[58:61]
	v_mfma_f32_16x16x32_bf16 v[62:65], v[154:157], v[182:185], v[62:65]
	v_mfma_f32_16x16x32_bf16 v[34:37], v[150:153], v[170:173], v[34:37]
	v_mfma_f32_16x16x32_bf16 v[30:33], v[158:161], v[170:173], v[30:33]
	v_mfma_f32_16x16x32_bf16 v[42:45], v[150:153], v[174:177], v[42:45]
	v_mfma_f32_16x16x32_bf16 v[46:49], v[158:161], v[174:177], v[46:49]
	v_mfma_f32_16x16x32_bf16 v[50:53], v[150:153], v[186:189], v[50:53]
	v_mfma_f32_16x16x32_bf16 v[54:57], v[158:161], v[186:189], v[54:57]
	v_mfma_f32_16x16x32_bf16 v[58:61], v[150:153], v[190:193], v[58:61]
	v_mfma_f32_16x16x32_bf16 v[62:65], v[158:161], v[190:193], v[62:65]
	s_barrier
	s_setprio 0
	s_add_i32 s4, s4, 2
	s_addk_i32 s5, 0x100
	s_cmp_gt_u32 s4, 61
	s_cbranch_scc0 .LBB0_1251
	s_and_b64 vcc, exec, s[18:19]
	s_cbranch_vccz .LBB0_1254
	s_barrier
